# SwiGLU epilogue rewritten: packed f32 math, per-wave LDS transpose so 4 lanes store 64 contiguous bytes
# speedup vs baseline: 1.1201x; 1.0029x over previous
; __device__ __forceinline__ unsigned cvt_pk_bf16(float lo, float hi) { f32x2_t v = {lo, hi}; bf16x2_t b = __builtin_convertvector(v, bf16x2_t); return __builtin_bit_cast(unsigned, b); }
; __device__ __forceinline__ float silu_mul(float a, float b) { return a * b * __builtin_amdgcn_rcpf(1.0f + __builtin_amdgcn_exp2f(a * -1.4426950408889634f)); }
;     __device__ __forceinline__ void operator()(const f32x4 (&acc)[2][2][4][2], const Unit& u, int wr, int wc, int fr, int fq, const float (&rr)[2][4]) const {
;         const int row0 = u.pm * BM + wr * 64 + fr, col0 = u.pn * 128 + wc * 32 + 8 * fq;
; #pragma unroll
;         for (int ai = 0; ai < 2; ++ai)
; #pragma unroll
;             for (int m = 0; m < 4; ++m) { const int row = row0 + ai * HALF + m * 16; const float r = rr[ai][m];
;                 const f32x4 g0 = acc[ai][0][m][0] * r, g1 = acc[ai][0][m][1] * r, u0 = acc[ai][1][m][0] * r, u1 = acc[ai][1][m][1] * r;
;                 u32x4 w; w.x = cvt_pk_bf16(silu_mul(g0[0], u0[0]), silu_mul(g0[1], u0[1])); w.y = cvt_pk_bf16(silu_mul(g0[2], u0[2]), silu_mul(g0[3], u0[3]));
;                 w.z = cvt_pk_bf16(silu_mul(g1[0], u1[0]), silu_mul(g1[1], u1[1])); w.w = cvt_pk_bf16(silu_mul(g1[2], u1[2]), silu_mul(g1[3], u1[3]));
;                 *(u32x4*)(O + (size_t)row * ldc + col0) = w; }
.LBB0_616:
	s_lshl_b32 s6, s23, 8
	s_add_i32 s6, s6, s2
	s_movk_i32 s8, 0x1600
	v_and_b32_e32 v155, 24, v153
	v_lshl_or_b32 v155, v155, 1, v141
	v_lshrrev_b32_e32 v150, 2, v155
	v_and_b32_e32 v152, 3, v155
	v_lshrrev_b32_e32 v146, 4, v155
	v_lshrrev_b32_e32 v148, 2, v141
	v_xor_b32_e32 v146, v146, v148
	v_lshlrev_b32_e32 v146, 4, v146
	v_lshl_or_b32 v146, v141, 6, v146
	v_add_u32_e32 v146, s3, v146
	v_add_u32_e32 v146, 0x23000, v146
	v_lshrrev_b32_e32 v148, 2, v150
	v_xor_b32_e32 v148, v148, v152
	v_lshlrev_b32_e32 v148, 4, v148
	v_lshl_or_b32 v148, v150, 6, v148
	v_add_u32_e32 v148, s3, v148
	v_add_u32_e32 v148, 0x23000, v148
	v_add_u32_e32 v150, s6, v150
	v_mul_lo_u32 v150, v150, s8
	v_and_b32_e32 v158, 0x60, v153
	v_lshl_or_b32 v158, s22, 7, v158
	v_lshlrev_b32_e32 v158, 1, v158
	v_lshl_or_b32 v158, v152, 4, v158
	v_mov_b32_e32 v159, 0
	v_add_u32_e32 v158, v158, v150
	v_mov_b32_e32 v156, 1.0
	v_mov_b32_e32 v157, 1.0
	v_lshl_add_u64 v[158:159], s[56:57], 0, v[158:159]
	v_cvt_f32_f16_e32 v140, v143
	v_pk_mul_f32 v[118:119], v[126:127], v[118:119]
	v_pk_mul_f32 v[120:121], v[128:129], v[120:121]
	v_pk_mul_f32 v[114:115], v[122:123], v[114:115]
	v_pk_mul_f32 v[116:117], v[124:125], v[116:117]
	v_mul_f32_e32 v142, 0xbfb8aa3b, v140
	v_mul_f32_e32 v144, v140, v140
	v_pk_mul_f32 v[126:127], v[126:127], v[142:143] op_sel_hi:[1,0]
	v_pk_mul_f32 v[128:129], v[128:129], v[142:143] op_sel_hi:[1,0]
	v_pk_mul_f32 v[122:123], v[122:123], v[142:143] op_sel_hi:[1,0]
	v_pk_mul_f32 v[124:125], v[124:125], v[142:143] op_sel_hi:[1,0]
	v_exp_f32_e32 v126, v126
	v_exp_f32_e32 v127, v127
	v_exp_f32_e32 v128, v128
	v_exp_f32_e32 v129, v129
	v_exp_f32_e32 v122, v122
	v_exp_f32_e32 v123, v123
	v_exp_f32_e32 v124, v124
	v_exp_f32_e32 v125, v125
	v_pk_mul_f32 v[118:119], v[118:119], v[144:145] op_sel_hi:[1,0]
	v_pk_mul_f32 v[120:121], v[120:121], v[144:145] op_sel_hi:[1,0]
	v_pk_mul_f32 v[114:115], v[114:115], v[144:145] op_sel_hi:[1,0]
	v_pk_mul_f32 v[116:117], v[116:117], v[144:145] op_sel_hi:[1,0]
	v_pk_add_f32 v[126:127], v[126:127], v[156:157]
	v_pk_add_f32 v[128:129], v[128:129], v[156:157]
	v_pk_add_f32 v[122:123], v[122:123], v[156:157]
	v_pk_add_f32 v[124:125], v[124:125], v[156:157]
	v_rcp_f32_e32 v126, v126
	v_rcp_f32_e32 v127, v127
	v_rcp_f32_e32 v128, v128
	v_rcp_f32_e32 v129, v129
	v_rcp_f32_e32 v122, v122
	v_rcp_f32_e32 v123, v123
	v_rcp_f32_e32 v124, v124
	v_rcp_f32_e32 v125, v125
	s_nop 0
	v_pk_mul_f32 v[118:119], v[118:119], v[126:127]
	v_pk_mul_f32 v[120:121], v[120:121], v[128:129]
	v_pk_mul_f32 v[114:115], v[114:115], v[122:123]
	v_pk_mul_f32 v[116:117], v[116:117], v[124:125]
	v_cvt_pk_bf16_f32 v118, v118, v119
	v_cvt_pk_bf16_f32 v119, v120, v121
	v_cvt_pk_bf16_f32 v120, v114, v115
	v_cvt_pk_bf16_f32 v121, v116, v117
	ds_write_b128 v146, v[118:121]
	ds_read_b128 v[126:129], v148
	v_cvt_f32_f16_e32 v140, v145
	v_pk_mul_f32 v[102:103], v[110:111], v[102:103]
	v_pk_mul_f32 v[104:105], v[112:113], v[104:105]
	v_pk_mul_f32 v[98:99], v[106:107], v[98:99]
	v_pk_mul_f32 v[100:101], v[108:109], v[100:101]
	v_mul_f32_e32 v142, 0xbfb8aa3b, v140
	v_mul_f32_e32 v144, v140, v140
	v_pk_mul_f32 v[110:111], v[110:111], v[142:143] op_sel_hi:[1,0]
	v_pk_mul_f32 v[112:113], v[112:113], v[142:143] op_sel_hi:[1,0]
	v_pk_mul_f32 v[106:107], v[106:107], v[142:143] op_sel_hi:[1,0]
	v_pk_mul_f32 v[108:109], v[108:109], v[142:143] op_sel_hi:[1,0]
	v_exp_f32_e32 v110, v110
	v_exp_f32_e32 v111, v111
	v_exp_f32_e32 v112, v112
	v_exp_f32_e32 v113, v113
	v_exp_f32_e32 v106, v106
	v_exp_f32_e32 v107, v107
	v_exp_f32_e32 v108, v108
	v_exp_f32_e32 v109, v109
	v_pk_mul_f32 v[102:103], v[102:103], v[144:145] op_sel_hi:[1,0]
	v_pk_mul_f32 v[104:105], v[104:105], v[144:145] op_sel_hi:[1,0]
	v_pk_mul_f32 v[98:99], v[98:99], v[144:145] op_sel_hi:[1,0]
	v_pk_mul_f32 v[100:101], v[100:101], v[144:145] op_sel_hi:[1,0]
	v_pk_add_f32 v[110:111], v[110:111], v[156:157]
	v_pk_add_f32 v[112:113], v[112:113], v[156:157]
	v_pk_add_f32 v[106:107], v[106:107], v[156:157]
	v_pk_add_f32 v[108:109], v[108:109], v[156:157]
	v_rcp_f32_e32 v110, v110
	v_rcp_f32_e32 v111, v111
	v_rcp_f32_e32 v112, v112
	v_rcp_f32_e32 v113, v113
	v_rcp_f32_e32 v106, v106
	v_rcp_f32_e32 v107, v107
	v_rcp_f32_e32 v108, v108
	v_rcp_f32_e32 v109, v109
	s_waitcnt lgkmcnt(0)
	global_store_dwordx4 v[158:159], v[126:129], off
	v_pk_mul_f32 v[102:103], v[102:103], v[110:111]
	v_pk_mul_f32 v[104:105], v[104:105], v[112:113]
	v_pk_mul_f32 v[98:99], v[98:99], v[106:107]
	v_pk_mul_f32 v[100:101], v[100:101], v[108:109]
	v_cvt_pk_bf16_f32 v102, v102, v103
	v_cvt_pk_bf16_f32 v103, v104, v105
	v_cvt_pk_bf16_f32 v104, v98, v99
	v_cvt_pk_bf16_f32 v105, v100, v101
	ds_write_b128 v146, v[102:105]
	ds_read_b128 v[110:113], v148
	v_cvt_f32_f16_e32 v140, v147
	v_pk_mul_f32 v[86:87], v[94:95], v[86:87]
	v_pk_mul_f32 v[88:89], v[96:97], v[88:89]
	v_pk_mul_f32 v[82:83], v[90:91], v[82:83]
	v_pk_mul_f32 v[84:85], v[92:93], v[84:85]
	v_mul_f32_e32 v142, 0xbfb8aa3b, v140
	v_mul_f32_e32 v144, v140, v140
	v_pk_mul_f32 v[94:95], v[94:95], v[142:143] op_sel_hi:[1,0]
	v_pk_mul_f32 v[96:97], v[96:97], v[142:143] op_sel_hi:[1,0]
	v_pk_mul_f32 v[90:91], v[90:91], v[142:143] op_sel_hi:[1,0]
	v_pk_mul_f32 v[92:93], v[92:93], v[142:143] op_sel_hi:[1,0]
	v_exp_f32_e32 v94, v94
	v_exp_f32_e32 v95, v95
	v_exp_f32_e32 v96, v96
	v_exp_f32_e32 v97, v97
	v_exp_f32_e32 v90, v90
	v_exp_f32_e32 v91, v91
	v_exp_f32_e32 v92, v92
	v_exp_f32_e32 v93, v93
	v_pk_mul_f32 v[86:87], v[86:87], v[144:145] op_sel_hi:[1,0]
	v_pk_mul_f32 v[88:89], v[88:89], v[144:145] op_sel_hi:[1,0]
	v_pk_mul_f32 v[82:83], v[82:83], v[144:145] op_sel_hi:[1,0]
	v_pk_mul_f32 v[84:85], v[84:85], v[144:145] op_sel_hi:[1,0]
	v_pk_add_f32 v[94:95], v[94:95], v[156:157]
	v_pk_add_f32 v[96:97], v[96:97], v[156:157]
	v_pk_add_f32 v[90:91], v[90:91], v[156:157]
	v_pk_add_f32 v[92:93], v[92:93], v[156:157]
	v_rcp_f32_e32 v94, v94
	v_rcp_f32_e32 v95, v95
	v_rcp_f32_e32 v96, v96
	v_rcp_f32_e32 v97, v97
	v_rcp_f32_e32 v90, v90
	v_rcp_f32_e32 v91, v91
	v_rcp_f32_e32 v92, v92
	v_rcp_f32_e32 v93, v93
	s_mov_b64 s[6:7], 0x16000
	v_lshl_add_u64 v[158:159], v[158:159], 0, s[6:7]
	s_waitcnt lgkmcnt(0)
; __device__ __forceinline__ unsigned cvt_pk_bf16(float lo, float hi) { f32x2_t v = {lo, hi}; bf16x2_t b = __builtin_convertvector(v, bf16x2_t); return __builtin_bit_cast(unsigned, b); }
; __device__ __forceinline__ float silu_mul(float a, float b) { return a * b * __builtin_amdgcn_rcpf(1.0f + __builtin_amdgcn_exp2f(a * -1.4426950408889634f)); }
;     __device__ __forceinline__ void operator()(const f32x4 (&acc)[2][2][4][2], const Unit& u, int wr, int wc, int fr, int fq, const float (&rr)[2][4]) const {
;     ...
;         for (int ai = 0; ai < 2; ++ai)
; #pragma unroll
;             for (int m = 0; m < 4; ++m) { const int row = row0 + ai * HALF + m * 16; const float r = rr[ai][m];
;                 const f32x4 g0 = acc[ai][0][m][0] * r, g1 = acc[ai][0][m][1] * r, u0 = acc[ai][1][m][0] * r, u1 = acc[ai][1][m][1] * r;
;                 u32x4 w; w.x = cvt_pk_bf16(silu_mul(g0[0], u0[0]), silu_mul(g0[1], u0[1])); w.y = cvt_pk_bf16(silu_mul(g0[2], u0[2]), silu_mul(g0[3], u0[3]));
;                 w.z = cvt_pk_bf16(silu_mul(g1[0], u1[0]), silu_mul(g1[1], u1[1])); w.w = cvt_pk_bf16(silu_mul(g1[2], u1[2]), silu_mul(g1[3], u1[3]));
;                 *(u32x4*)(O + (size_t)row * ldc + col0) = w; }
	global_store_dwordx4 v[158:159], v[110:113], off
	v_pk_mul_f32 v[86:87], v[86:87], v[94:95]
	v_pk_mul_f32 v[88:89], v[88:89], v[96:97]
	v_pk_mul_f32 v[82:83], v[82:83], v[90:91]
	v_pk_mul_f32 v[84:85], v[84:85], v[92:93]
	v_cvt_pk_bf16_f32 v86, v86, v87
	v_cvt_pk_bf16_f32 v87, v88, v89
	v_cvt_pk_bf16_f32 v88, v82, v83
	v_cvt_pk_bf16_f32 v89, v84, v85
	ds_write_b128 v146, v[86:89]
	ds_read_b128 v[94:97], v148
	v_cvt_f32_f16_e32 v140, v149
	v_pk_mul_f32 v[70:71], v[78:79], v[70:71]
	v_pk_mul_f32 v[72:73], v[80:81], v[72:73]
	v_pk_mul_f32 v[66:67], v[74:75], v[66:67]
	v_pk_mul_f32 v[68:69], v[76:77], v[68:69]
	v_mul_f32_e32 v142, 0xbfb8aa3b, v140
	v_mul_f32_e32 v144, v140, v140
	v_pk_mul_f32 v[78:79], v[78:79], v[142:143] op_sel_hi:[1,0]
	v_pk_mul_f32 v[80:81], v[80:81], v[142:143] op_sel_hi:[1,0]
	v_pk_mul_f32 v[74:75], v[74:75], v[142:143] op_sel_hi:[1,0]
	v_pk_mul_f32 v[76:77], v[76:77], v[142:143] op_sel_hi:[1,0]
	v_exp_f32_e32 v78, v78
	v_exp_f32_e32 v79, v79
	v_exp_f32_e32 v80, v80
	v_exp_f32_e32 v81, v81
	v_exp_f32_e32 v74, v74
	v_exp_f32_e32 v75, v75
	v_exp_f32_e32 v76, v76
	v_exp_f32_e32 v77, v77
	v_pk_mul_f32 v[70:71], v[70:71], v[144:145] op_sel_hi:[1,0]
	v_pk_mul_f32 v[72:73], v[72:73], v[144:145] op_sel_hi:[1,0]
	v_pk_mul_f32 v[66:67], v[66:67], v[144:145] op_sel_hi:[1,0]
	v_pk_mul_f32 v[68:69], v[68:69], v[144:145] op_sel_hi:[1,0]
	v_pk_add_f32 v[78:79], v[78:79], v[156:157]
	v_pk_add_f32 v[80:81], v[80:81], v[156:157]
	v_pk_add_f32 v[74:75], v[74:75], v[156:157]
	v_pk_add_f32 v[76:77], v[76:77], v[156:157]
	v_rcp_f32_e32 v78, v78
	v_rcp_f32_e32 v79, v79
	v_rcp_f32_e32 v80, v80
	v_rcp_f32_e32 v81, v81
	v_rcp_f32_e32 v74, v74
	v_rcp_f32_e32 v75, v75
	v_rcp_f32_e32 v76, v76
	v_rcp_f32_e32 v77, v77
	s_mov_b64 s[6:7], 0x16000
	v_lshl_add_u64 v[158:159], v[158:159], 0, s[6:7]
	s_waitcnt lgkmcnt(0)
	global_store_dwordx4 v[158:159], v[94:97], off
	v_pk_mul_f32 v[70:71], v[70:71], v[78:79]
	v_pk_mul_f32 v[72:73], v[72:73], v[80:81]
	v_pk_mul_f32 v[66:67], v[66:67], v[74:75]
	v_pk_mul_f32 v[68:69], v[68:69], v[76:77]
	v_cvt_pk_bf16_f32 v70, v70, v71
	v_cvt_pk_bf16_f32 v71, v72, v73
	v_cvt_pk_bf16_f32 v72, v66, v67
	v_cvt_pk_bf16_f32 v73, v68, v69
	ds_write_b128 v146, v[70:73]
	ds_read_b128 v[78:81], v148
	v_cvt_f32_f16_sdwa v140, v143 dst_sel:DWORD dst_unused:UNUSED_PAD src0_sel:WORD_1
	v_pk_mul_f32 v[54:55], v[62:63], v[54:55]
	v_pk_mul_f32 v[56:57], v[64:65], v[56:57]
	v_pk_mul_f32 v[50:51], v[58:59], v[50:51]
	v_pk_mul_f32 v[52:53], v[60:61], v[52:53]
	v_mul_f32_e32 v142, 0xbfb8aa3b, v140
	v_mul_f32_e32 v144, v140, v140
	v_pk_mul_f32 v[62:63], v[62:63], v[142:143] op_sel_hi:[1,0]
	v_pk_mul_f32 v[64:65], v[64:65], v[142:143] op_sel_hi:[1,0]
	v_pk_mul_f32 v[58:59], v[58:59], v[142:143] op_sel_hi:[1,0]
	v_pk_mul_f32 v[60:61], v[60:61], v[142:143] op_sel_hi:[1,0]
	v_exp_f32_e32 v62, v62
	v_exp_f32_e32 v63, v63
	v_exp_f32_e32 v64, v64
	v_exp_f32_e32 v65, v65
	v_exp_f32_e32 v58, v58
	v_exp_f32_e32 v59, v59
	v_exp_f32_e32 v60, v60
	v_exp_f32_e32 v61, v61
	v_pk_mul_f32 v[54:55], v[54:55], v[144:145] op_sel_hi:[1,0]
	v_pk_mul_f32 v[56:57], v[56:57], v[144:145] op_sel_hi:[1,0]
	v_pk_mul_f32 v[50:51], v[50:51], v[144:145] op_sel_hi:[1,0]
	v_pk_mul_f32 v[52:53], v[52:53], v[144:145] op_sel_hi:[1,0]
	v_pk_add_f32 v[62:63], v[62:63], v[156:157]
	v_pk_add_f32 v[64:65], v[64:65], v[156:157]
	v_pk_add_f32 v[58:59], v[58:59], v[156:157]
	v_pk_add_f32 v[60:61], v[60:61], v[156:157]
	v_rcp_f32_e32 v62, v62
	v_rcp_f32_e32 v63, v63
	v_rcp_f32_e32 v64, v64
	v_rcp_f32_e32 v65, v65
	v_rcp_f32_e32 v58, v58
	v_rcp_f32_e32 v59, v59
	v_rcp_f32_e32 v60, v60
	v_rcp_f32_e32 v61, v61
	s_mov_b64 s[6:7], 0x16000
	v_lshl_add_u64 v[158:159], v[158:159], 0, s[6:7]
	s_waitcnt lgkmcnt(0)
	global_store_dwordx4 v[158:159], v[78:81], off
	v_pk_mul_f32 v[54:55], v[54:55], v[62:63]
	v_pk_mul_f32 v[56:57], v[56:57], v[64:65]
	v_pk_mul_f32 v[50:51], v[50:51], v[58:59]
	v_pk_mul_f32 v[52:53], v[52:53], v[60:61]
	v_cvt_pk_bf16_f32 v54, v54, v55
	v_cvt_pk_bf16_f32 v55, v56, v57
	v_cvt_pk_bf16_f32 v56, v50, v51
	v_cvt_pk_bf16_f32 v57, v52, v53
	ds_write_b128 v146, v[54:57]
	ds_read_b128 v[62:65], v148
	v_cvt_f32_f16_sdwa v140, v145 dst_sel:DWORD dst_unused:UNUSED_PAD src0_sel:WORD_1
	v_pk_mul_f32 v[38:39], v[46:47], v[38:39]
	v_pk_mul_f32 v[40:41], v[48:49], v[40:41]
	v_pk_mul_f32 v[34:35], v[42:43], v[34:35]
	v_pk_mul_f32 v[36:37], v[44:45], v[36:37]
	v_mul_f32_e32 v142, 0xbfb8aa3b, v140
	v_mul_f32_e32 v144, v140, v140
	v_pk_mul_f32 v[46:47], v[46:47], v[142:143] op_sel_hi:[1,0]
	v_pk_mul_f32 v[48:49], v[48:49], v[142:143] op_sel_hi:[1,0]
	v_pk_mul_f32 v[42:43], v[42:43], v[142:143] op_sel_hi:[1,0]
	v_pk_mul_f32 v[44:45], v[44:45], v[142:143] op_sel_hi:[1,0]
	v_exp_f32_e32 v46, v46
	v_exp_f32_e32 v47, v47
	v_exp_f32_e32 v48, v48
	v_exp_f32_e32 v49, v49
	v_exp_f32_e32 v42, v42
	v_exp_f32_e32 v43, v43
	v_exp_f32_e32 v44, v44
	v_exp_f32_e32 v45, v45
	v_pk_mul_f32 v[38:39], v[38:39], v[144:145] op_sel_hi:[1,0]
	v_pk_mul_f32 v[40:41], v[40:41], v[144:145] op_sel_hi:[1,0]
	v_pk_mul_f32 v[34:35], v[34:35], v[144:145] op_sel_hi:[1,0]
	v_pk_mul_f32 v[36:37], v[36:37], v[144:145] op_sel_hi:[1,0]
	v_pk_add_f32 v[46:47], v[46:47], v[156:157]
	v_pk_add_f32 v[48:49], v[48:49], v[156:157]
	v_pk_add_f32 v[42:43], v[42:43], v[156:157]
	v_pk_add_f32 v[44:45], v[44:45], v[156:157]
	v_rcp_f32_e32 v46, v46
	v_rcp_f32_e32 v47, v47
	v_rcp_f32_e32 v48, v48
	v_rcp_f32_e32 v49, v49
	v_rcp_f32_e32 v42, v42
	v_rcp_f32_e32 v43, v43
	v_rcp_f32_e32 v44, v44
	v_rcp_f32_e32 v45, v45
	s_mov_b64 s[6:7], 0x6e000
	v_lshl_add_u64 v[158:159], v[158:159], 0, s[6:7]
	s_waitcnt lgkmcnt(0)
; __device__ __forceinline__ unsigned cvt_pk_bf16(float lo, float hi) { f32x2_t v = {lo, hi}; bf16x2_t b = __builtin_convertvector(v, bf16x2_t); return __builtin_bit_cast(unsigned, b); }
; __device__ __forceinline__ float silu_mul(float a, float b) { return a * b * __builtin_amdgcn_rcpf(1.0f + __builtin_amdgcn_exp2f(a * -1.4426950408889634f)); }
;     __device__ __forceinline__ void operator()(const f32x4 (&acc)[2][2][4][2], const Unit& u, int wr, int wc, int fr, int fq, const float (&rr)[2][4]) const {
;     ...
;         for (int ai = 0; ai < 2; ++ai)
; #pragma unroll
;             for (int m = 0; m < 4; ++m) { const int row = row0 + ai * HALF + m * 16; const float r = rr[ai][m];
;                 const f32x4 g0 = acc[ai][0][m][0] * r, g1 = acc[ai][0][m][1] * r, u0 = acc[ai][1][m][0] * r, u1 = acc[ai][1][m][1] * r;
;                 u32x4 w; w.x = cvt_pk_bf16(silu_mul(g0[0], u0[0]), silu_mul(g0[1], u0[1])); w.y = cvt_pk_bf16(silu_mul(g0[2], u0[2]), silu_mul(g0[3], u0[3]));
;                 w.z = cvt_pk_bf16(silu_mul(g1[0], u1[0]), silu_mul(g1[1], u1[1])); w.w = cvt_pk_bf16(silu_mul(g1[2], u1[2]), silu_mul(g1[3], u1[3]));
;                 *(u32x4*)(O + (size_t)row * ldc + col0) = w; }
	global_store_dwordx4 v[158:159], v[62:65], off
	v_pk_mul_f32 v[38:39], v[38:39], v[46:47]
	v_pk_mul_f32 v[40:41], v[40:41], v[48:49]
	v_pk_mul_f32 v[34:35], v[34:35], v[42:43]
	v_pk_mul_f32 v[36:37], v[36:37], v[44:45]
	v_cvt_pk_bf16_f32 v38, v38, v39
	v_cvt_pk_bf16_f32 v39, v40, v41
	v_cvt_pk_bf16_f32 v40, v34, v35
	v_cvt_pk_bf16_f32 v41, v36, v37
	ds_write_b128 v146, v[38:41]
	ds_read_b128 v[46:49], v148
	v_cvt_f32_f16_sdwa v140, v147 dst_sel:DWORD dst_unused:UNUSED_PAD src0_sel:WORD_1
	v_pk_mul_f32 v[22:23], v[30:31], v[22:23]
	v_pk_mul_f32 v[24:25], v[32:33], v[24:25]
	v_pk_mul_f32 v[18:19], v[26:27], v[18:19]
	v_pk_mul_f32 v[20:21], v[28:29], v[20:21]
	v_mul_f32_e32 v142, 0xbfb8aa3b, v140
	v_mul_f32_e32 v144, v140, v140
	v_pk_mul_f32 v[30:31], v[30:31], v[142:143] op_sel_hi:[1,0]
	v_pk_mul_f32 v[32:33], v[32:33], v[142:143] op_sel_hi:[1,0]
	v_pk_mul_f32 v[26:27], v[26:27], v[142:143] op_sel_hi:[1,0]
	v_pk_mul_f32 v[28:29], v[28:29], v[142:143] op_sel_hi:[1,0]
	v_exp_f32_e32 v30, v30
	v_exp_f32_e32 v31, v31
	v_exp_f32_e32 v32, v32
	v_exp_f32_e32 v33, v33
	v_exp_f32_e32 v26, v26
	v_exp_f32_e32 v27, v27
	v_exp_f32_e32 v28, v28
	v_exp_f32_e32 v29, v29
	v_pk_mul_f32 v[22:23], v[22:23], v[144:145] op_sel_hi:[1,0]
	v_pk_mul_f32 v[24:25], v[24:25], v[144:145] op_sel_hi:[1,0]
	v_pk_mul_f32 v[18:19], v[18:19], v[144:145] op_sel_hi:[1,0]
	v_pk_mul_f32 v[20:21], v[20:21], v[144:145] op_sel_hi:[1,0]
	v_pk_add_f32 v[30:31], v[30:31], v[156:157]
	v_pk_add_f32 v[32:33], v[32:33], v[156:157]
	v_pk_add_f32 v[26:27], v[26:27], v[156:157]
	v_pk_add_f32 v[28:29], v[28:29], v[156:157]
	v_rcp_f32_e32 v30, v30
	v_rcp_f32_e32 v31, v31
	v_rcp_f32_e32 v32, v32
	v_rcp_f32_e32 v33, v33
	v_rcp_f32_e32 v26, v26
	v_rcp_f32_e32 v27, v27
	v_rcp_f32_e32 v28, v28
	v_rcp_f32_e32 v29, v29
	s_mov_b64 s[6:7], 0x16000
	v_lshl_add_u64 v[158:159], v[158:159], 0, s[6:7]
	s_waitcnt lgkmcnt(0)
	global_store_dwordx4 v[158:159], v[46:49], off
	v_pk_mul_f32 v[22:23], v[22:23], v[30:31]
	v_pk_mul_f32 v[24:25], v[24:25], v[32:33]
	v_pk_mul_f32 v[18:19], v[18:19], v[26:27]
	v_pk_mul_f32 v[20:21], v[20:21], v[28:29]
	v_cvt_pk_bf16_f32 v22, v22, v23
	v_cvt_pk_bf16_f32 v23, v24, v25
	v_cvt_pk_bf16_f32 v24, v18, v19
	v_cvt_pk_bf16_f32 v25, v20, v21
	ds_write_b128 v146, v[22:25]
	ds_read_b128 v[30:33], v148
	v_cvt_f32_f16_sdwa v140, v149 dst_sel:DWORD dst_unused:UNUSED_PAD src0_sel:WORD_1
	v_pk_mul_f32 v[6:7], v[14:15], v[6:7]
	v_pk_mul_f32 v[8:9], v[16:17], v[8:9]
	v_pk_mul_f32 v[2:3], v[10:11], v[2:3]
	v_pk_mul_f32 v[4:5], v[12:13], v[4:5]
	v_mul_f32_e32 v142, 0xbfb8aa3b, v140
	v_mul_f32_e32 v144, v140, v140
	v_pk_mul_f32 v[14:15], v[14:15], v[142:143] op_sel_hi:[1,0]
	v_pk_mul_f32 v[16:17], v[16:17], v[142:143] op_sel_hi:[1,0]
	v_pk_mul_f32 v[10:11], v[10:11], v[142:143] op_sel_hi:[1,0]
	v_pk_mul_f32 v[12:13], v[12:13], v[142:143] op_sel_hi:[1,0]
	v_exp_f32_e32 v14, v14
	v_exp_f32_e32 v15, v15
	v_exp_f32_e32 v16, v16
	v_exp_f32_e32 v17, v17
	v_exp_f32_e32 v10, v10
	v_exp_f32_e32 v11, v11
	v_exp_f32_e32 v12, v12
	v_exp_f32_e32 v13, v13
	v_pk_mul_f32 v[6:7], v[6:7], v[144:145] op_sel_hi:[1,0]
	v_pk_mul_f32 v[8:9], v[8:9], v[144:145] op_sel_hi:[1,0]
	v_pk_mul_f32 v[2:3], v[2:3], v[144:145] op_sel_hi:[1,0]
	v_pk_mul_f32 v[4:5], v[4:5], v[144:145] op_sel_hi:[1,0]
	v_pk_add_f32 v[14:15], v[14:15], v[156:157]
	v_pk_add_f32 v[16:17], v[16:17], v[156:157]
	v_pk_add_f32 v[10:11], v[10:11], v[156:157]
	v_pk_add_f32 v[12:13], v[12:13], v[156:157]
	v_rcp_f32_e32 v14, v14
	v_rcp_f32_e32 v15, v15
	v_rcp_f32_e32 v16, v16
	v_rcp_f32_e32 v17, v17
	v_rcp_f32_e32 v10, v10
	v_rcp_f32_e32 v11, v11
	v_rcp_f32_e32 v12, v12
	v_rcp_f32_e32 v13, v13
	s_mov_b64 s[6:7], 0x16000
	v_lshl_add_u64 v[158:159], v[158:159], 0, s[6:7]
	s_waitcnt lgkmcnt(0)
	global_store_dwordx4 v[158:159], v[30:33], off
	v_pk_mul_f32 v[6:7], v[6:7], v[14:15]
	v_pk_mul_f32 v[8:9], v[8:9], v[16:17]
	v_pk_mul_f32 v[2:3], v[2:3], v[10:11]
	v_pk_mul_f32 v[4:5], v[4:5], v[12:13]
	v_cvt_pk_bf16_f32 v6, v6, v7
	v_cvt_pk_bf16_f32 v7, v8, v9
	v_cvt_pk_bf16_f32 v8, v2, v3
	v_cvt_pk_bf16_f32 v9, v4, v5
	ds_write_b128 v146, v[6:9]
	ds_read_b128 v[14:17], v148
	s_mov_b64 s[6:7], 0x16000
	v_lshl_add_u64 v[158:159], v[158:159], 0, s[6:7]
	s_waitcnt lgkmcnt(0)
	global_store_dwordx4 v[158:159], v[14:17], off
	s_and_b64 vcc, exec, s[38:39]
	s_mov_b64 s[6:7], -1
	s_cbranch_vccnz .LBB0_604
	s_andn2_b64 vcc, exec, s[72:73]
	s_cbranch_vccnz .LBB0_603
	s_barrier
	s_branch .LBB0_603
